# scan-phase weight conversion: same-wave LDS transpose wait dropped
# baseline (speedup 1.0000x reference)
.LBB0_852:
	s_add_u32 s36, s52, s36
	s_addc_u32 s37, s53, s37
	s_lshl_b32 s54, vcc_lo, 7
	s_and_b32 s67, s66, 64
	s_and_b32 s54, s54, 0xffffff00
	s_or_b32 s47, s67, s47
	s_or_b32 s47, s47, s54
	s_and_b64 s[34:35], s[34:35], exec
	s_waitcnt vmcnt(14)
	v_cvt_pk_bf16_f32 v108, v108, v112
	v_cvt_pk_bf16_f32 v109, v109, v113
	v_cvt_pk_bf16_f32 v110, v110, v114
	v_cvt_pk_bf16_f32 v111, v111, v115
	ds_write_b128 v156, v[108:111]
	s_waitcnt vmcnt(12)
	v_cvt_pk_bf16_f32 v100, v100, v104
	v_cvt_pk_bf16_f32 v101, v101, v105
	v_cvt_pk_bf16_f32 v102, v102, v106
	v_cvt_pk_bf16_f32 v103, v103, v107
	ds_write_b128 v156, v[100:103] offset:1088
	s_waitcnt vmcnt(10)
	v_cvt_pk_bf16_f32 v92, v92, v96
	v_cvt_pk_bf16_f32 v93, v93, v97
	v_cvt_pk_bf16_f32 v94, v94, v98
	v_cvt_pk_bf16_f32 v95, v95, v99
	ds_write_b128 v156, v[92:95] offset:2176
	s_waitcnt vmcnt(8)
	v_cvt_pk_bf16_f32 v84, v84, v88
	v_cvt_pk_bf16_f32 v85, v85, v89
	v_cvt_pk_bf16_f32 v86, v86, v90
	v_cvt_pk_bf16_f32 v87, v87, v91
	ds_write_b128 v156, v[84:87] offset:3264
	s_waitcnt vmcnt(6)
	v_cvt_pk_bf16_f32 v76, v76, v80
	v_cvt_pk_bf16_f32 v77, v77, v81
	v_cvt_pk_bf16_f32 v78, v78, v82
	v_cvt_pk_bf16_f32 v79, v79, v83
	ds_write_b128 v156, v[76:79] offset:4352
	s_waitcnt vmcnt(4)
	v_cvt_pk_bf16_f32 v68, v68, v72
	v_cvt_pk_bf16_f32 v69, v69, v73
	v_cvt_pk_bf16_f32 v70, v70, v74
	v_cvt_pk_bf16_f32 v71, v71, v75
	ds_write_b128 v156, v[68:71] offset:5440
	s_waitcnt vmcnt(2)
	v_cvt_pk_bf16_f32 v60, v60, v64
	v_cvt_pk_bf16_f32 v61, v61, v65
	v_cvt_pk_bf16_f32 v62, v62, v66
	v_cvt_pk_bf16_f32 v63, v63, v67
	ds_write_b128 v156, v[60:63] offset:6528
	s_waitcnt vmcnt(0)
	v_cvt_pk_bf16_f32 v52, v52, v56
	v_cvt_pk_bf16_f32 v53, v53, v57
	v_cvt_pk_bf16_f32 v54, v54, v58
	v_cvt_pk_bf16_f32 v55, v55, v59
	ds_write_b128 v156, v[52:55] offset:7616
	s_cselect_b32 s47, s66, s47
	s_lshl_b64 s[34:35], s[64:65], 1
	s_add_u32 s34, s36, s34
	s_addc_u32 s35, s37, s35
	v_mov_b32_e32 v125, v119
	ds_read_b128 v[52:55], v157
	ds_read_b128 v[56:59], v157 offset:272
	ds_read_b128 v[60:63], v157 offset:544
	ds_read_b128 v[64:67], v157 offset:816
	v_or_b32_e32 v76, s47, v146
	v_lshl_add_u64 v[72:73], s[34:35], 0, v[124:125]
	v_mad_u64_u32 v[74:75], s[34:35], s30, v76, 0
	s_ashr_i32 s34, s47, 31
	s_waitcnt lgkmcnt(3)
	v_mov_b32_e32 v68, v52
	v_mul_lo_u32 v52, s31, v76
	s_mul_i32 s36, s30, s34
	v_add3_u32 v75, v75, s36, v52
	s_waitcnt lgkmcnt(2)
	v_mov_b32_e32 v69, v56
	s_waitcnt lgkmcnt(1)
	v_mov_b32_e32 v70, v60
	s_waitcnt lgkmcnt(0)
	v_mov_b32_e32 v71, v64
	v_lshl_add_u64 v[74:75], v[74:75], 1, v[72:73]
	v_or_b32_e32 v52, 1, v76
	global_store_dwordx4 v[74:75], v[68:71], off
	v_mul_lo_u32 v56, s31, v52
	v_mov_b32_e32 v64, v55
	v_mov_b32_e32 v68, v53
	v_mad_u64_u32 v[52:53], s[34:35], s30, v52, 0
	v_add3_u32 v53, v53, s36, v56
	v_mov_b32_e32 v69, v57
	v_mov_b32_e32 v70, v61
	v_mov_b32_e32 v71, v65
	v_lshl_add_u64 v[52:53], v[52:53], 1, v[72:73]
	global_store_dwordx4 v[52:53], v[68:71], off
	v_or_b32_e32 v52, 2, v76
	v_mov_b32_e32 v65, v59
	v_mov_b32_e32 v68, v54
	v_mul_lo_u32 v54, s31, v52
	v_mad_u64_u32 v[52:53], s[34:35], s30, v52, 0
	v_add3_u32 v53, v53, s36, v54
	v_mov_b32_e32 v69, v58
	v_mov_b32_e32 v70, v62
	v_mov_b32_e32 v71, v66
	v_lshl_add_u64 v[52:53], v[52:53], 1, v[72:73]
	global_store_dwordx4 v[52:53], v[68:71], off
	v_or_b32_e32 v52, 3, v76
	v_mul_lo_u32 v54, s31, v52
	v_mad_u64_u32 v[52:53], s[34:35], s30, v52, 0
	v_add3_u32 v53, v53, s36, v54
	v_mov_b32_e32 v66, v63
	v_lshl_add_u64 v[52:53], v[52:53], 1, v[72:73]
	global_store_dwordx4 v[52:53], v[64:67], off
	ds_read_b128 v[52:55], v158
	ds_read_b128 v[56:59], v158 offset:272
	ds_read_b128 v[60:63], v158 offset:544
	ds_read_b128 v[64:67], v158 offset:816
	v_or_b32_e32 v76, s47, v147
	s_waitcnt lgkmcnt(3)
	v_mov_b32_e32 v68, v52
	v_mul_lo_u32 v52, s31, v76
	v_mad_u64_u32 v[74:75], s[34:35], s30, v76, 0
	v_add3_u32 v75, v75, s36, v52
	s_waitcnt lgkmcnt(2)
	v_mov_b32_e32 v69, v56
	s_waitcnt lgkmcnt(1)
	v_mov_b32_e32 v70, v60
	s_waitcnt lgkmcnt(0)
	v_mov_b32_e32 v71, v64
	v_lshl_add_u64 v[74:75], v[74:75], 1, v[72:73]
	v_or_b32_e32 v52, 1, v76
	global_store_dwordx4 v[74:75], v[68:71], off
	v_mul_lo_u32 v56, s31, v52
	v_mov_b32_e32 v64, v55
	v_mov_b32_e32 v68, v53
	v_mad_u64_u32 v[52:53], s[34:35], s30, v52, 0
	v_add3_u32 v53, v53, s36, v56
	v_mov_b32_e32 v69, v57
	v_mov_b32_e32 v70, v61
	v_mov_b32_e32 v71, v65
	v_lshl_add_u64 v[52:53], v[52:53], 1, v[72:73]
	global_store_dwordx4 v[52:53], v[68:71], off
	v_or_b32_e32 v52, 2, v76
	v_mov_b32_e32 v65, v59
	v_mov_b32_e32 v68, v54
	v_mul_lo_u32 v54, s31, v52
	v_mad_u64_u32 v[52:53], s[34:35], s30, v52, 0
	v_add3_u32 v53, v53, s36, v54
	v_mov_b32_e32 v69, v58
	v_mov_b32_e32 v70, v62
	v_mov_b32_e32 v71, v66
	v_lshl_add_u64 v[52:53], v[52:53], 1, v[72:73]
	global_store_dwordx4 v[52:53], v[68:71], off
	v_or_b32_e32 v52, 3, v76
	v_mul_lo_u32 v54, s31, v52
	v_mad_u64_u32 v[52:53], s[30:31], s30, v52, 0
	v_add3_u32 v53, v53, s36, v54
	v_mov_b32_e32 v66, v63
	v_lshl_add_u64 v[52:53], v[52:53], 1, v[72:73]
	global_store_dwordx4 v[52:53], v[64:67], off
	s_waitcnt lgkmcnt(0)
	s_add_i32 s80, s80, s88
	s_cmpk_gt_i32 s80, 0x12ff
	s_cbranch_scc1 .LBB0_867
